# 8-phase GEMM accumulator zero-init with 64-bit moves
# speedup vs baseline: 1.0129x; 1.0055x over previous
.LBB0_108:
	s_or_b64 exec, exec, s[70:71]
	v_readlane_b32 s4, v254, 9
	s_mov_b64 s[6:7], 0x80
	v_lshl_add_u64 v[4:5], v[0:1], 0, s[6:7]
	v_add_u32_e32 v144, s4, v193
	v_add_u32_e32 v145, 0x2000, v144
	v_readfirstlane_b32 s38, v144
	s_mov_b32 m0, s38
	s_mov_b64 s[4:5], 0x58080
	v_readfirstlane_b32 s38, v145
	s_waitcnt vmcnt(4)
	s_barrier
	global_load_lds_dwordx4 v[4:5], off
	v_lshl_add_u64 v[4:5], v[0:1], 0, s[4:5]
	s_mov_b32 m0, s38
	v_add_u32_e32 v146, 0x8000, v130
	global_load_lds_dwordx4 v[4:5], off
	v_lshl_add_u64 v[4:5], v[2:3], 0, s[6:7]
	v_readfirstlane_b32 s38, v146
	v_lshl_add_u64 v[2:3], v[2:3], 0, s[4:5]
	v_add_u32_e32 v147, 0xa000, v130
	v_readlane_b32 s4, v254, 10
	s_mov_b32 m0, s38
	v_readfirstlane_b32 s38, v147
	v_add_u32_e32 v148, s4, v193
	global_load_lds_dwordx4 v[4:5], off
	s_mov_b32 m0, s38
	s_mov_b64 s[6:7], 0xb0080
	v_readfirstlane_b32 s38, v148
	v_add_u32_e32 v149, 0x2000, v148
	global_load_lds_dwordx4 v[2:3], off
	v_lshl_add_u64 v[2:3], v[0:1], 0, s[6:7]
	s_mov_b32 m0, s38
	s_mov_b64 s[4:5], 0x108080
	v_readfirstlane_b32 s38, v149
	global_load_lds_dwordx4 v[2:3], off
	v_lshl_add_u64 v[0:1], v[0:1], 0, s[4:5]
	s_mov_b32 m0, s38
	s_add_u32 s48, s92, s48
	global_load_lds_dwordx4 v[0:1], off
	s_addc_u32 s49, s93, s49
	s_add_i32 s35, s34, s35
	s_mul_hi_i32 s38, s35, 0x1600
	s_mulk_i32 s35, 0x1600
	s_add_u32 s70, s92, s35
	v_mov_b32_e32 v0, 0
	s_addc_u32 s71, s93, s38
	s_mov_b32 s35, -2
	v_mov_b32_e32 v1, v0
	v_mov_b64_e32 v[2:3], v[0:1]
	v_mov_b64_e32 v[4:5], v[0:1]
	v_mov_b64_e32 v[6:7], v[0:1]
	v_mov_b64_e32 v[8:9], v[0:1]
	v_mov_b64_e32 v[10:11], v[0:1]
	v_mov_b64_e32 v[12:13], v[0:1]
	v_mov_b64_e32 v[14:15], v[0:1]
	v_mov_b64_e32 v[16:17], v[0:1]
	v_mov_b64_e32 v[18:19], v[0:1]
	v_mov_b64_e32 v[20:21], v[0:1]
	v_mov_b64_e32 v[22:23], v[0:1]
	v_mov_b64_e32 v[24:25], v[0:1]
	v_mov_b64_e32 v[26:27], v[0:1]
	v_mov_b64_e32 v[28:29], v[0:1]
	v_mov_b64_e32 v[30:31], v[0:1]
	v_mov_b64_e32 v[32:33], v[0:1]
	v_mov_b64_e32 v[34:35], v[0:1]
	v_mov_b64_e32 v[36:37], v[0:1]
	v_mov_b64_e32 v[38:39], v[0:1]
	v_mov_b64_e32 v[40:41], v[0:1]
	v_mov_b64_e32 v[42:43], v[0:1]
	v_mov_b64_e32 v[44:45], v[0:1]
	v_mov_b64_e32 v[46:47], v[0:1]
	v_mov_b64_e32 v[48:49], v[0:1]
	v_mov_b64_e32 v[50:51], v[0:1]
	v_mov_b64_e32 v[52:53], v[0:1]
	v_mov_b64_e32 v[54:55], v[0:1]
	v_mov_b64_e32 v[56:57], v[0:1]
	v_mov_b64_e32 v[58:59], v[0:1]
	v_mov_b64_e32 v[60:61], v[0:1]
	v_mov_b64_e32 v[62:63], v[0:1]
	v_mov_b64_e32 v[64:65], v[0:1]
	v_mov_b64_e32 v[66:67], v[0:1]
	v_mov_b64_e32 v[68:69], v[0:1]
	v_mov_b64_e32 v[70:71], v[0:1]
	v_mov_b64_e32 v[72:73], v[0:1]
	v_mov_b64_e32 v[74:75], v[0:1]
	v_mov_b64_e32 v[76:77], v[0:1]
	v_mov_b64_e32 v[78:79], v[0:1]
	v_mov_b64_e32 v[80:81], v[0:1]
	v_mov_b64_e32 v[82:83], v[0:1]
	v_mov_b64_e32 v[84:85], v[0:1]
	v_mov_b64_e32 v[86:87], v[0:1]
	v_mov_b64_e32 v[88:89], v[0:1]
	v_mov_b64_e32 v[90:91], v[0:1]
	v_mov_b64_e32 v[92:93], v[0:1]
	v_mov_b64_e32 v[94:95], v[0:1]
	v_mov_b64_e32 v[96:97], v[0:1]
	v_mov_b64_e32 v[98:99], v[0:1]
	v_mov_b64_e32 v[100:101], v[0:1]
	v_mov_b64_e32 v[102:103], v[0:1]
	v_mov_b64_e32 v[104:105], v[0:1]
	v_mov_b64_e32 v[106:107], v[0:1]
	v_mov_b64_e32 v[108:109], v[0:1]
	v_mov_b64_e32 v[110:111], v[0:1]
	v_mov_b64_e32 v[112:113], v[0:1]
	v_mov_b64_e32 v[114:115], v[0:1]
	v_mov_b64_e32 v[116:117], v[0:1]
	v_mov_b64_e32 v[118:119], v[0:1]
	v_mov_b64_e32 v[120:121], v[0:1]
	v_mov_b64_e32 v[122:123], v[0:1]
	v_mov_b64_e32 v[124:125], v[0:1]
	v_mov_b64_e32 v[126:127], v[0:1]
	s_mov_b64 s[8:9], 0x180
	s_waitcnt vmcnt(6)
	s_barrier

.Lgu_join:
	v_mov_b32_e32 v1, v0
	v_mov_b64_e32 v[2:3], v[0:1]
	v_mov_b64_e32 v[4:5], v[0:1]
	v_mov_b64_e32 v[6:7], v[0:1]
	v_mov_b64_e32 v[8:9], v[0:1]
	v_mov_b64_e32 v[10:11], v[0:1]
	v_mov_b64_e32 v[12:13], v[0:1]
	v_mov_b64_e32 v[14:15], v[0:1]
	v_mov_b64_e32 v[16:17], v[0:1]
	v_mov_b64_e32 v[18:19], v[0:1]
	v_mov_b64_e32 v[20:21], v[0:1]
	v_mov_b64_e32 v[22:23], v[0:1]
	v_mov_b64_e32 v[24:25], v[0:1]
	v_mov_b64_e32 v[26:27], v[0:1]
	v_mov_b64_e32 v[28:29], v[0:1]
	v_mov_b64_e32 v[30:31], v[0:1]
	v_mov_b64_e32 v[32:33], v[0:1]
	v_mov_b64_e32 v[34:35], v[0:1]
	v_mov_b64_e32 v[36:37], v[0:1]
	v_mov_b64_e32 v[38:39], v[0:1]
	v_mov_b64_e32 v[40:41], v[0:1]
	v_mov_b64_e32 v[42:43], v[0:1]
	v_mov_b64_e32 v[44:45], v[0:1]
	v_mov_b64_e32 v[46:47], v[0:1]
	v_mov_b64_e32 v[48:49], v[0:1]
	v_mov_b64_e32 v[50:51], v[0:1]
	v_mov_b64_e32 v[52:53], v[0:1]
	v_mov_b64_e32 v[54:55], v[0:1]
	v_mov_b64_e32 v[56:57], v[0:1]
	v_mov_b64_e32 v[58:59], v[0:1]
	v_mov_b64_e32 v[60:61], v[0:1]
	v_mov_b64_e32 v[62:63], v[0:1]
	v_mov_b64_e32 v[64:65], v[0:1]
	v_mov_b64_e32 v[66:67], v[0:1]
	v_mov_b64_e32 v[68:69], v[0:1]
	v_mov_b64_e32 v[70:71], v[0:1]
	v_mov_b64_e32 v[72:73], v[0:1]
	v_mov_b64_e32 v[74:75], v[0:1]
	v_mov_b64_e32 v[76:77], v[0:1]
	v_mov_b64_e32 v[78:79], v[0:1]
	v_mov_b64_e32 v[80:81], v[0:1]
	v_mov_b64_e32 v[82:83], v[0:1]
	v_mov_b64_e32 v[84:85], v[0:1]
	v_mov_b64_e32 v[86:87], v[0:1]
	v_mov_b64_e32 v[88:89], v[0:1]
	v_mov_b64_e32 v[90:91], v[0:1]
	v_mov_b64_e32 v[92:93], v[0:1]
	v_mov_b64_e32 v[94:95], v[0:1]
	v_mov_b64_e32 v[96:97], v[0:1]
	v_mov_b64_e32 v[98:99], v[0:1]
	v_mov_b64_e32 v[100:101], v[0:1]
	v_mov_b64_e32 v[102:103], v[0:1]
	v_mov_b64_e32 v[104:105], v[0:1]
	v_mov_b64_e32 v[106:107], v[0:1]
	v_mov_b64_e32 v[108:109], v[0:1]
	v_mov_b64_e32 v[110:111], v[0:1]
	v_mov_b64_e32 v[112:113], v[0:1]
	v_mov_b64_e32 v[114:115], v[0:1]
	v_mov_b64_e32 v[116:117], v[0:1]
	v_mov_b64_e32 v[118:119], v[0:1]
	v_mov_b64_e32 v[120:121], v[0:1]
	v_mov_b64_e32 v[122:123], v[0:1]
	v_mov_b64_e32 v[124:125], v[0:1]
	v_mov_b64_e32 v[126:127], v[0:1]
	s_mov_b64 s[4:5], 0x8440080
	s_mov_b64 s[6:7], 0x8460080
	s_mov_b64 s[8:9], 0x8400100
	s_mov_b64 s[10:11], 0x8420100
	s_mov_b64 s[38:39], 0x8440100
	s_mov_b64 s[16:17], 0x8460100
	s_mov_b64 s[18:19], 0x8400180
	s_barrier

.LBB0_281:
	s_or_b64 exec, exec, s[70:71]
	v_readlane_b32 s3, v254, 9
	s_mov_b64 s[4:5], 0x80
	v_lshl_add_u64 v[6:7], v[0:1], 0, s[4:5]
	v_add_u32_e32 v146, s3, v150
	v_add_u32_e32 v147, 0x2000, v146
	v_readfirstlane_b32 s3, v146
	s_mov_b32 m0, s3
	s_mov_b64 s[6:7], 0x20080
	v_readfirstlane_b32 s3, v147
	v_add_u32_e32 v148, 0x8000, v134
	s_waitcnt vmcnt(4)
	s_barrier
	global_load_lds_dwordx4 v[6:7], off
	v_lshl_add_u64 v[0:1], v[0:1], 0, s[6:7]
	s_mov_b32 m0, s3
	v_readfirstlane_b32 s3, v148
	v_add_u32_e32 v149, 0xa000, v134
	global_load_lds_dwordx4 v[0:1], off
	v_lshl_add_u64 v[0:1], v[2:3], 0, s[4:5]
	s_mov_b32 m0, s3
	v_readfirstlane_b32 s3, v149
	global_load_lds_dwordx4 v[0:1], off
	s_mov_b32 m0, s3
	v_readlane_b32 s3, v254, 10
	v_lshl_add_u64 v[0:1], v[2:3], 0, s[6:7]
	global_load_lds_dwordx4 v[0:1], off
	v_add_u32_e32 v161, s3, v150
	v_add_u32_e32 v162, 0x2000, v161
	v_readfirstlane_b32 s3, v161
	v_lshl_add_u64 v[0:1], v[4:5], 0, s[4:5]
	s_mov_b32 m0, s3
	v_readfirstlane_b32 s3, v162
	global_load_lds_dwordx4 v[0:1], off
	v_lshl_add_u64 v[0:1], v[4:5], 0, s[6:7]
	s_mov_b32 m0, s3
	s_add_u32 s48, s92, s48
	global_load_lds_dwordx4 v[0:1], off
	s_addc_u32 s49, s93, s49
	s_add_i32 s34, s22, s23
	s_ashr_i32 s35, s34, 31
	s_lshl_b64 s[34:35], s[34:35], 11
	s_add_u32 s70, s92, s34
	v_mov_b32_e32 v0, 0
	s_addc_u32 s71, s93, s35
	s_mov_b32 s3, -2
	v_mov_b32_e32 v1, v0
	v_mov_b64_e32 v[2:3], v[0:1]
	v_mov_b64_e32 v[4:5], v[0:1]
	v_mov_b64_e32 v[6:7], v[0:1]
	v_mov_b64_e32 v[8:9], v[0:1]
	v_mov_b64_e32 v[10:11], v[0:1]
	v_mov_b64_e32 v[12:13], v[0:1]
	v_mov_b64_e32 v[14:15], v[0:1]
	v_mov_b64_e32 v[16:17], v[0:1]
	v_mov_b64_e32 v[18:19], v[0:1]
	v_mov_b64_e32 v[20:21], v[0:1]
	v_mov_b64_e32 v[22:23], v[0:1]
	v_mov_b64_e32 v[24:25], v[0:1]
	v_mov_b64_e32 v[26:27], v[0:1]
	v_mov_b64_e32 v[28:29], v[0:1]
	v_mov_b64_e32 v[30:31], v[0:1]
	v_mov_b64_e32 v[32:33], v[0:1]
	v_mov_b64_e32 v[34:35], v[0:1]
	v_mov_b64_e32 v[36:37], v[0:1]
	v_mov_b64_e32 v[38:39], v[0:1]
	v_mov_b64_e32 v[40:41], v[0:1]
	v_mov_b64_e32 v[42:43], v[0:1]
	v_mov_b64_e32 v[44:45], v[0:1]
	v_mov_b64_e32 v[46:47], v[0:1]
	v_mov_b64_e32 v[48:49], v[0:1]
	v_mov_b64_e32 v[50:51], v[0:1]
	v_mov_b64_e32 v[52:53], v[0:1]
	v_mov_b64_e32 v[54:55], v[0:1]
	v_mov_b64_e32 v[56:57], v[0:1]
	v_mov_b64_e32 v[58:59], v[0:1]
	v_mov_b64_e32 v[60:61], v[0:1]
	v_mov_b64_e32 v[62:63], v[0:1]
	v_mov_b64_e32 v[64:65], v[0:1]
	v_mov_b64_e32 v[66:67], v[0:1]
	v_mov_b64_e32 v[68:69], v[0:1]
	v_mov_b64_e32 v[70:71], v[0:1]
	v_mov_b64_e32 v[72:73], v[0:1]
	v_mov_b64_e32 v[74:75], v[0:1]
	v_mov_b64_e32 v[76:77], v[0:1]
	v_mov_b64_e32 v[78:79], v[0:1]
	v_mov_b64_e32 v[80:81], v[0:1]
	v_mov_b64_e32 v[82:83], v[0:1]
	v_mov_b64_e32 v[84:85], v[0:1]
	v_mov_b64_e32 v[86:87], v[0:1]
	v_mov_b64_e32 v[88:89], v[0:1]
	v_mov_b64_e32 v[90:91], v[0:1]
	v_mov_b64_e32 v[92:93], v[0:1]
	v_mov_b64_e32 v[94:95], v[0:1]
	v_mov_b64_e32 v[96:97], v[0:1]
	v_mov_b64_e32 v[98:99], v[0:1]
	v_mov_b64_e32 v[100:101], v[0:1]
	v_mov_b64_e32 v[102:103], v[0:1]
	v_mov_b64_e32 v[104:105], v[0:1]
	v_mov_b64_e32 v[106:107], v[0:1]
	v_mov_b64_e32 v[108:109], v[0:1]
	v_mov_b64_e32 v[110:111], v[0:1]
	v_mov_b64_e32 v[112:113], v[0:1]
	v_mov_b64_e32 v[114:115], v[0:1]
	v_mov_b64_e32 v[116:117], v[0:1]
	v_mov_b64_e32 v[118:119], v[0:1]
	v_mov_b64_e32 v[120:121], v[0:1]
	v_mov_b64_e32 v[122:123], v[0:1]
	v_mov_b64_e32 v[124:125], v[0:1]
	v_mov_b64_e32 v[126:127], v[0:1]
	s_mov_b64 s[4:5], 0x8440080
	s_mov_b64 s[6:7], 0x8460080
	s_mov_b64 s[8:9], 0x8400100
	s_mov_b64 s[10:11], 0x8420100
	s_mov_b64 s[34:35], 0x8440100
	s_mov_b64 s[38:39], 0x149c0100
	s_mov_b64 s[76:77], 0x149e0100
	s_mov_b64 s[78:79], 0x14a00100
	s_mov_b64 s[80:81], 0x14a20100
	s_mov_b64 s[82:83], 0x149c0180
	s_mov_b64 s[90:91], 0x149e0180
	s_mov_b64 s[16:17], 0x14a00180
	s_mov_b64 s[18:19], 0x14a20180
	s_mov_b64 s[46:47], 0x8460100
	s_mov_b64 s[50:51], 0x8400180
	s_waitcnt vmcnt(6)
	s_barrier

.LBB0_323:
	s_or_b64 exec, exec, s[48:49]
	v_readlane_b32 s1, v254, 9
	s_mov_b64 s[4:5], 0x80
	v_lshl_add_u64 v[6:7], v[0:1], 0, s[4:5]
	v_add_u32_e32 v157, s1, v142
	v_add_u32_e32 v158, 0x2000, v157
	v_readfirstlane_b32 s1, v157
	s_mov_b32 m0, s1
	s_mov_b64 s[6:7], 0x20080
	v_readfirstlane_b32 s1, v158
	v_add_u32_e32 v159, 0x8000, v134
	s_waitcnt vmcnt(4)
	s_barrier
	global_load_lds_dwordx4 v[6:7], off
	v_lshl_add_u64 v[0:1], v[0:1], 0, s[6:7]
	s_mov_b32 m0, s1
	v_readfirstlane_b32 s1, v159
	v_add_u32_e32 v160, 0xa000, v134
	global_load_lds_dwordx4 v[0:1], off
	v_lshl_add_u64 v[0:1], v[2:3], 0, s[4:5]
	s_mov_b32 m0, s1
	v_readfirstlane_b32 s1, v160
	global_load_lds_dwordx4 v[0:1], off
	s_mov_b32 m0, s1
	v_readlane_b32 s1, v254, 10
	v_lshl_add_u64 v[0:1], v[2:3], 0, s[6:7]
	global_load_lds_dwordx4 v[0:1], off
	v_add_u32_e32 v161, s1, v142
	v_add_u32_e32 v162, 0x2000, v161
	v_readfirstlane_b32 s1, v161
	v_lshl_add_u64 v[0:1], v[4:5], 0, s[4:5]
	s_mov_b32 m0, s1
	v_readfirstlane_b32 s1, v162
	global_load_lds_dwordx4 v[0:1], off
	v_lshl_add_u64 v[0:1], v[4:5], 0, s[6:7]
	s_mov_b32 m0, s1
	s_add_u32 s44, s92, s44
	global_load_lds_dwordx4 v[0:1], off
	s_addc_u32 s45, s93, s45
	s_add_i32 s22, s23, s22
	s_ashr_i32 s23, s22, 31
	s_lshl_b64 s[22:23], s[22:23], 11
	s_add_u32 s48, s92, s22
	v_mov_b32_e32 v0, 0
	s_addc_u32 s49, s93, s23
	s_mov_b32 s1, -2
	v_mov_b32_e32 v1, v0
	v_mov_b64_e32 v[2:3], v[0:1]
	v_mov_b64_e32 v[4:5], v[0:1]
	v_mov_b64_e32 v[6:7], v[0:1]
	v_mov_b64_e32 v[8:9], v[0:1]
	v_mov_b64_e32 v[10:11], v[0:1]
	v_mov_b64_e32 v[12:13], v[0:1]
	v_mov_b64_e32 v[14:15], v[0:1]
	v_mov_b64_e32 v[16:17], v[0:1]
	v_mov_b64_e32 v[18:19], v[0:1]
	v_mov_b64_e32 v[20:21], v[0:1]
	v_mov_b64_e32 v[22:23], v[0:1]
	v_mov_b64_e32 v[24:25], v[0:1]
	v_mov_b64_e32 v[26:27], v[0:1]
	v_mov_b64_e32 v[28:29], v[0:1]
	v_mov_b64_e32 v[30:31], v[0:1]
	v_mov_b64_e32 v[32:33], v[0:1]
	v_mov_b64_e32 v[34:35], v[0:1]
	v_mov_b64_e32 v[36:37], v[0:1]
	v_mov_b64_e32 v[38:39], v[0:1]
	v_mov_b64_e32 v[40:41], v[0:1]
	v_mov_b64_e32 v[42:43], v[0:1]
	v_mov_b64_e32 v[44:45], v[0:1]
	v_mov_b64_e32 v[46:47], v[0:1]
	v_mov_b64_e32 v[48:49], v[0:1]
	v_mov_b64_e32 v[50:51], v[0:1]
	v_mov_b64_e32 v[52:53], v[0:1]
	v_mov_b64_e32 v[54:55], v[0:1]
	v_mov_b64_e32 v[56:57], v[0:1]
	v_mov_b64_e32 v[58:59], v[0:1]
	v_mov_b64_e32 v[60:61], v[0:1]
	v_mov_b64_e32 v[62:63], v[0:1]
	v_mov_b64_e32 v[64:65], v[0:1]
	v_mov_b64_e32 v[66:67], v[0:1]
	v_mov_b64_e32 v[68:69], v[0:1]
	v_mov_b64_e32 v[70:71], v[0:1]
	v_mov_b64_e32 v[72:73], v[0:1]
	v_mov_b64_e32 v[74:75], v[0:1]
	v_mov_b64_e32 v[76:77], v[0:1]
	v_mov_b64_e32 v[78:79], v[0:1]
	v_mov_b64_e32 v[80:81], v[0:1]
	v_mov_b64_e32 v[82:83], v[0:1]
	v_mov_b64_e32 v[84:85], v[0:1]
	v_mov_b64_e32 v[86:87], v[0:1]
	v_mov_b64_e32 v[88:89], v[0:1]
	v_mov_b64_e32 v[90:91], v[0:1]
	v_mov_b64_e32 v[92:93], v[0:1]
	v_mov_b64_e32 v[94:95], v[0:1]
	v_mov_b64_e32 v[96:97], v[0:1]
	v_mov_b64_e32 v[98:99], v[0:1]
	v_mov_b64_e32 v[100:101], v[0:1]
	v_mov_b64_e32 v[102:103], v[0:1]
	v_mov_b64_e32 v[104:105], v[0:1]
	v_mov_b64_e32 v[106:107], v[0:1]
	v_mov_b64_e32 v[108:109], v[0:1]
	v_mov_b64_e32 v[110:111], v[0:1]
	v_mov_b64_e32 v[112:113], v[0:1]
	v_mov_b64_e32 v[114:115], v[0:1]
	v_mov_b64_e32 v[116:117], v[0:1]
	v_mov_b64_e32 v[118:119], v[0:1]
	v_mov_b64_e32 v[120:121], v[0:1]
	v_mov_b64_e32 v[122:123], v[0:1]
	v_mov_b64_e32 v[124:125], v[0:1]
	v_mov_b64_e32 v[126:127], v[0:1]
	s_mov_b64 s[4:5], 0x8440080
	s_mov_b64 s[6:7], 0x8460080
	s_mov_b64 s[8:9], 0x8400100
	s_mov_b64 s[10:11], 0x8420100
	s_mov_b64 s[14:15], 0x8440100
	s_mov_b64 s[12:13], 0x14420100
	s_mov_b64 s[16:17], 0x14440100
	s_mov_b64 s[18:19], 0x14460100
	s_mov_b64 s[22:23], 0x14480100
	s_mov_b64 s[34:35], 0x14420180
	s_mov_b64 s[38:39], 0x14440180
	s_mov_b64 s[72:73], 0x14460180
	s_mov_b64 s[76:77], 0x14480180
	s_mov_b64 s[46:47], 0x8460100
	s_mov_b64 s[50:51], 0x8400180
	s_waitcnt vmcnt(6)
	s_barrier

.LBB0_339:
	s_or_b64 exec, exec, s[70:71]
	v_readlane_b32 s3, v254, 9
	s_mov_b64 s[4:5], 0x80
	v_lshl_add_u64 v[6:7], v[0:1], 0, s[4:5]
	v_add_u32_e32 v146, s3, v150
	v_add_u32_e32 v147, 0x2000, v146
	v_readfirstlane_b32 s3, v146
	s_mov_b32 m0, s3
	s_mov_b64 s[6:7], 0x20080
	v_readfirstlane_b32 s3, v147
	v_add_u32_e32 v148, 0x8000, v134
	s_waitcnt vmcnt(4)
	s_barrier
	global_load_lds_dwordx4 v[6:7], off
	v_lshl_add_u64 v[0:1], v[0:1], 0, s[6:7]
	s_mov_b32 m0, s3
	v_readfirstlane_b32 s3, v148
	v_add_u32_e32 v149, 0xa000, v134
	global_load_lds_dwordx4 v[0:1], off
	v_lshl_add_u64 v[0:1], v[2:3], 0, s[4:5]
	s_mov_b32 m0, s3
	v_readfirstlane_b32 s3, v149
	global_load_lds_dwordx4 v[0:1], off
	s_mov_b32 m0, s3
	v_readlane_b32 s3, v254, 10
	v_lshl_add_u64 v[0:1], v[2:3], 0, s[6:7]
	global_load_lds_dwordx4 v[0:1], off
	v_add_u32_e32 v161, s3, v150
	v_add_u32_e32 v162, 0x2000, v161
	v_readfirstlane_b32 s3, v161
	v_lshl_add_u64 v[0:1], v[4:5], 0, s[4:5]
	s_mov_b32 m0, s3
	v_readfirstlane_b32 s3, v162
	global_load_lds_dwordx4 v[0:1], off
	v_lshl_add_u64 v[0:1], v[4:5], 0, s[6:7]
	s_mov_b32 m0, s3
	s_add_u32 s48, s92, s48
	global_load_lds_dwordx4 v[0:1], off
	s_addc_u32 s49, s93, s49
	s_add_i32 s34, s22, s23
	s_ashr_i32 s35, s34, 31
	s_lshl_b64 s[34:35], s[34:35], 11
	s_add_u32 s70, s92, s34
	v_mov_b32_e32 v0, 0
	s_addc_u32 s71, s93, s35
	s_mov_b32 s3, -2
	v_mov_b32_e32 v1, v0
	v_mov_b64_e32 v[2:3], v[0:1]
	v_mov_b64_e32 v[4:5], v[0:1]
	v_mov_b64_e32 v[6:7], v[0:1]
	v_mov_b64_e32 v[8:9], v[0:1]
	v_mov_b64_e32 v[10:11], v[0:1]
	v_mov_b64_e32 v[12:13], v[0:1]
	v_mov_b64_e32 v[14:15], v[0:1]
	v_mov_b64_e32 v[16:17], v[0:1]
	v_mov_b64_e32 v[18:19], v[0:1]
	v_mov_b64_e32 v[20:21], v[0:1]
	v_mov_b64_e32 v[22:23], v[0:1]
	v_mov_b64_e32 v[24:25], v[0:1]
	v_mov_b64_e32 v[26:27], v[0:1]
	v_mov_b64_e32 v[28:29], v[0:1]
	v_mov_b64_e32 v[30:31], v[0:1]
	v_mov_b64_e32 v[32:33], v[0:1]
	v_mov_b64_e32 v[34:35], v[0:1]
	v_mov_b64_e32 v[36:37], v[0:1]
	v_mov_b64_e32 v[38:39], v[0:1]
	v_mov_b64_e32 v[40:41], v[0:1]
	v_mov_b64_e32 v[42:43], v[0:1]
	v_mov_b64_e32 v[44:45], v[0:1]
	v_mov_b64_e32 v[46:47], v[0:1]
	v_mov_b64_e32 v[48:49], v[0:1]
	v_mov_b64_e32 v[50:51], v[0:1]
	v_mov_b64_e32 v[52:53], v[0:1]
	v_mov_b64_e32 v[54:55], v[0:1]
	v_mov_b64_e32 v[56:57], v[0:1]
	v_mov_b64_e32 v[58:59], v[0:1]
	v_mov_b64_e32 v[60:61], v[0:1]
	v_mov_b64_e32 v[62:63], v[0:1]
	v_mov_b64_e32 v[64:65], v[0:1]
	v_mov_b64_e32 v[66:67], v[0:1]
	v_mov_b64_e32 v[68:69], v[0:1]
	v_mov_b64_e32 v[70:71], v[0:1]
	v_mov_b64_e32 v[72:73], v[0:1]
	v_mov_b64_e32 v[74:75], v[0:1]
	v_mov_b64_e32 v[76:77], v[0:1]
	v_mov_b64_e32 v[78:79], v[0:1]
	v_mov_b64_e32 v[80:81], v[0:1]
	v_mov_b64_e32 v[82:83], v[0:1]
	v_mov_b64_e32 v[84:85], v[0:1]
	v_mov_b64_e32 v[86:87], v[0:1]
	v_mov_b64_e32 v[88:89], v[0:1]
	v_mov_b64_e32 v[90:91], v[0:1]
	v_mov_b64_e32 v[92:93], v[0:1]
	v_mov_b64_e32 v[94:95], v[0:1]
	v_mov_b64_e32 v[96:97], v[0:1]
	v_mov_b64_e32 v[98:99], v[0:1]
	v_mov_b64_e32 v[100:101], v[0:1]
	v_mov_b64_e32 v[102:103], v[0:1]
	v_mov_b64_e32 v[104:105], v[0:1]
	v_mov_b64_e32 v[106:107], v[0:1]
	v_mov_b64_e32 v[108:109], v[0:1]
	v_mov_b64_e32 v[110:111], v[0:1]
	v_mov_b64_e32 v[112:113], v[0:1]
	v_mov_b64_e32 v[114:115], v[0:1]
	v_mov_b64_e32 v[116:117], v[0:1]
	v_mov_b64_e32 v[118:119], v[0:1]
	v_mov_b64_e32 v[120:121], v[0:1]
	v_mov_b64_e32 v[122:123], v[0:1]
	v_mov_b64_e32 v[124:125], v[0:1]
	v_mov_b64_e32 v[126:127], v[0:1]
	s_mov_b64 s[4:5], 0x149c0100
	s_mov_b64 s[6:7], 0x149e0100
	s_mov_b64 s[34:35], 0x14a00100
	s_mov_b64 s[76:77], 0x14a20100
	s_mov_b64 s[78:79], 0x149c0180
	s_mov_b64 s[80:81], 0x149e0180
	s_mov_b64 s[82:83], 0x14a00180
	s_mov_b64 s[16:17], 0x14a20180
	s_waitcnt vmcnt(6)
	s_barrier

.LBB0_1050:
	s_or_b64 exec, exec, s[48:49]
	v_readlane_b32 s1, v254, 9
	s_mov_b64 s[4:5], 0x80
	v_lshl_add_u64 v[6:7], v[0:1], 0, s[4:5]
	v_add_u32_e32 v157, s1, v132
	v_add_u32_e32 v158, 0x2000, v157
	v_readfirstlane_b32 s1, v157
	s_mov_b32 m0, s1
	s_mov_b64 s[6:7], 0x20080
	v_readfirstlane_b32 s1, v158
	v_add_u32_e32 v159, 0x8000, v151
	s_waitcnt vmcnt(4)
	s_barrier
	global_load_lds_dwordx4 v[6:7], off
	v_lshl_add_u64 v[0:1], v[0:1], 0, s[6:7]
	s_mov_b32 m0, s1
	v_readfirstlane_b32 s1, v159
	v_add_u32_e32 v160, 0xa000, v151
	global_load_lds_dwordx4 v[0:1], off
	v_lshl_add_u64 v[0:1], v[2:3], 0, s[4:5]
	s_mov_b32 m0, s1
	v_readfirstlane_b32 s1, v160
	global_load_lds_dwordx4 v[0:1], off
	s_mov_b32 m0, s1
	v_readlane_b32 s1, v254, 10
	v_lshl_add_u64 v[0:1], v[2:3], 0, s[6:7]
	global_load_lds_dwordx4 v[0:1], off
	v_add_u32_e32 v161, s1, v132
	v_add_u32_e32 v162, 0x2000, v161
	v_readfirstlane_b32 s1, v161
	v_lshl_add_u64 v[0:1], v[4:5], 0, s[4:5]
	s_mov_b32 m0, s1
	v_readfirstlane_b32 s1, v162
	global_load_lds_dwordx4 v[0:1], off
	v_lshl_add_u64 v[0:1], v[4:5], 0, s[6:7]
	s_mov_b32 m0, s1
	s_add_u32 s44, s92, s44
	global_load_lds_dwordx4 v[0:1], off
	s_addc_u32 s45, s93, s45
	s_add_i32 s34, s35, s34
	s_ashr_i32 s35, s34, 31
	s_lshl_b64 s[34:35], s[34:35], 11
	s_add_u32 s48, s92, s34
	v_mov_b32_e32 v0, 0
	s_addc_u32 s49, s93, s35
	s_mov_b32 s1, -2
	v_mov_b32_e32 v1, v0
	v_mov_b64_e32 v[2:3], v[0:1]
	v_mov_b64_e32 v[4:5], v[0:1]
	v_mov_b64_e32 v[6:7], v[0:1]
	v_mov_b64_e32 v[8:9], v[0:1]
	v_mov_b64_e32 v[10:11], v[0:1]
	v_mov_b64_e32 v[12:13], v[0:1]
	v_mov_b64_e32 v[14:15], v[0:1]
	v_mov_b64_e32 v[16:17], v[0:1]
	v_mov_b64_e32 v[18:19], v[0:1]
	v_mov_b64_e32 v[20:21], v[0:1]
	v_mov_b64_e32 v[22:23], v[0:1]
	v_mov_b64_e32 v[24:25], v[0:1]
	v_mov_b64_e32 v[26:27], v[0:1]
	v_mov_b64_e32 v[28:29], v[0:1]
	v_mov_b64_e32 v[30:31], v[0:1]
	v_mov_b64_e32 v[32:33], v[0:1]
	v_mov_b64_e32 v[34:35], v[0:1]
	v_mov_b64_e32 v[36:37], v[0:1]
	v_mov_b64_e32 v[38:39], v[0:1]
	v_mov_b64_e32 v[40:41], v[0:1]
	v_mov_b64_e32 v[42:43], v[0:1]
	v_mov_b64_e32 v[44:45], v[0:1]
	v_mov_b64_e32 v[46:47], v[0:1]
	v_mov_b64_e32 v[48:49], v[0:1]
	v_mov_b64_e32 v[50:51], v[0:1]
	v_mov_b64_e32 v[52:53], v[0:1]
	v_mov_b64_e32 v[54:55], v[0:1]
	v_mov_b64_e32 v[56:57], v[0:1]
	v_mov_b64_e32 v[58:59], v[0:1]
	v_mov_b64_e32 v[60:61], v[0:1]
	v_mov_b64_e32 v[62:63], v[0:1]
	v_mov_b64_e32 v[64:65], v[0:1]
	v_mov_b64_e32 v[66:67], v[0:1]
	v_mov_b64_e32 v[68:69], v[0:1]
	v_mov_b64_e32 v[70:71], v[0:1]
	v_mov_b64_e32 v[72:73], v[0:1]
	v_mov_b64_e32 v[74:75], v[0:1]
	v_mov_b64_e32 v[76:77], v[0:1]
	v_mov_b64_e32 v[78:79], v[0:1]
	v_mov_b64_e32 v[80:81], v[0:1]
	v_mov_b64_e32 v[82:83], v[0:1]
	v_mov_b64_e32 v[84:85], v[0:1]
	v_mov_b64_e32 v[86:87], v[0:1]
	v_mov_b64_e32 v[88:89], v[0:1]
	v_mov_b64_e32 v[90:91], v[0:1]
	v_mov_b64_e32 v[92:93], v[0:1]
	v_mov_b64_e32 v[94:95], v[0:1]
	v_mov_b64_e32 v[96:97], v[0:1]
	v_mov_b64_e32 v[98:99], v[0:1]
	v_mov_b64_e32 v[100:101], v[0:1]
	v_mov_b64_e32 v[102:103], v[0:1]
	v_mov_b64_e32 v[104:105], v[0:1]
	v_mov_b64_e32 v[106:107], v[0:1]
	v_mov_b64_e32 v[108:109], v[0:1]
	v_mov_b64_e32 v[110:111], v[0:1]
	v_mov_b64_e32 v[112:113], v[0:1]
	v_mov_b64_e32 v[114:115], v[0:1]
	v_mov_b64_e32 v[116:117], v[0:1]
	v_mov_b64_e32 v[118:119], v[0:1]
	v_mov_b64_e32 v[120:121], v[0:1]
	v_mov_b64_e32 v[122:123], v[0:1]
	v_mov_b64_e32 v[124:125], v[0:1]
	v_mov_b64_e32 v[126:127], v[0:1]
	s_mov_b64 s[4:5], 0x8440080
	s_mov_b64 s[6:7], 0x8460080
	s_mov_b64 s[8:9], 0x8400100
	s_mov_b64 s[10:11], 0x8420100
	s_mov_b64 s[14:15], 0x8440100
	s_mov_b64 s[12:13], 0x14420100
	s_mov_b64 s[16:17], 0x14440100
	s_mov_b64 s[18:19], 0x14460100
	s_mov_b64 s[34:35], 0x14480100
	s_mov_b64 s[38:39], 0x14420180
	s_mov_b64 s[70:71], 0x14440180
	s_mov_b64 s[72:73], 0x14460180
	s_mov_b64 s[74:75], 0x14480180
	s_mov_b64 s[46:47], 0x8460100
	s_mov_b64 s[50:51], 0x8400180
	s_waitcnt vmcnt(6)
	s_barrier
